# prologue: non-temporal (nt) hint on the read-once f32 weight and x loads
# speedup vs baseline: 1.0444x; 1.0262x over previous
.LBB0_70:
	v_mov_b32_e32 v5, v2
	s_sext_i32_i16 s35, s35
	v_cmp_lt_i32_e32 vcc, -1, v4
	v_lshl_add_u64 v[74:75], v[4:5], 2, s[52:53]
	v_mov_b32_e32 v4, v2
	s_lshl_b32 s54, s35, 6
	v_mov_b32_e32 v3, v2
	v_mov_b64_e32 v[8:9], v[4:5]
	v_or_b32_e32 v72, s54, v76
	v_mov_b64_e32 v[6:7], v[2:3]
	s_and_saveexec_b64 s[52:53], vcc
	s_cbranch_execz .LBB0_72
	v_mul_hi_i32_i24_e32 v7, s34, v72
	v_mul_i32_i24_e32 v6, s34, v72
	v_lshl_add_u64 v[6:7], v[6:7], 2, v[74:75]
	global_load_dwordx4 v[6:9], v[6:7], off nt
.LBB0_72:
	s_or_b64 exec, exec, s[52:53]
	v_mov_b64_e32 v[12:13], v[4:5]
	v_mov_b64_e32 v[10:11], v[2:3]
	s_and_saveexec_b64 s[52:53], vcc
	s_cbranch_execz .LBB0_74
	v_or_b32_e32 v3, 4, v72
	v_mul_hi_i32_i24_e32 v5, s34, v3
	v_mul_i32_i24_e32 v4, s34, v3
	v_lshl_add_u64 v[4:5], v[4:5], 2, v[74:75]
	global_load_dwordx4 v[10:13], v[4:5], off nt
.LBB0_74:
	s_or_b64 exec, exec, s[52:53]
	v_mov_b32_e32 v4, v2
	v_mov_b32_e32 v5, v2
	v_mov_b32_e32 v3, v2
	v_mov_b64_e32 v[16:17], v[4:5]
	v_mov_b64_e32 v[14:15], v[2:3]
	s_and_saveexec_b64 s[52:53], vcc
	s_cbranch_execz .LBB0_76
	v_or_b32_e32 v14, 8, v72
	v_mul_hi_i32_i24_e32 v15, s34, v14
	v_mul_i32_i24_e32 v14, s34, v14
	v_lshl_add_u64 v[14:15], v[14:15], 2, v[74:75]
	global_load_dwordx4 v[14:17], v[14:15], off nt
.LBB0_76:
	s_or_b64 exec, exec, s[52:53]
	v_mov_b64_e32 v[20:21], v[4:5]
	v_mov_b64_e32 v[18:19], v[2:3]
	s_and_saveexec_b64 s[52:53], vcc
	s_cbranch_execz .LBB0_78
	v_or_b32_e32 v3, 12, v72
	v_mul_hi_i32_i24_e32 v5, s34, v3
	v_mul_i32_i24_e32 v4, s34, v3
	v_lshl_add_u64 v[4:5], v[4:5], 2, v[74:75]
	global_load_dwordx4 v[18:21], v[4:5], off nt
.LBB0_78:
	s_or_b64 exec, exec, s[52:53]
	v_mov_b32_e32 v4, v2
	v_mov_b32_e32 v5, v2
	v_mov_b32_e32 v3, v2
	v_mov_b64_e32 v[24:25], v[4:5]
	v_mov_b64_e32 v[22:23], v[2:3]
	s_and_saveexec_b64 s[52:53], vcc
	s_cbranch_execz .LBB0_80
	v_or_b32_e32 v22, 16, v72
	v_mul_hi_i32_i24_e32 v23, s34, v22
	v_mul_i32_i24_e32 v22, s34, v22
	v_lshl_add_u64 v[22:23], v[22:23], 2, v[74:75]
	global_load_dwordx4 v[22:25], v[22:23], off nt
.LBB0_80:
	s_or_b64 exec, exec, s[52:53]
	v_mov_b64_e32 v[28:29], v[4:5]
	v_mov_b64_e32 v[26:27], v[2:3]
	s_and_saveexec_b64 s[52:53], vcc
	s_cbranch_execz .LBB0_82
	v_or_b32_e32 v3, 20, v72
	v_mul_hi_i32_i24_e32 v5, s34, v3
	v_mul_i32_i24_e32 v4, s34, v3
	v_lshl_add_u64 v[4:5], v[4:5], 2, v[74:75]
	global_load_dwordx4 v[26:29], v[4:5], off nt
.LBB0_82:
	s_or_b64 exec, exec, s[52:53]
	v_mov_b32_e32 v4, v2
	v_mov_b32_e32 v5, v2
	v_mov_b32_e32 v3, v2
	v_mov_b64_e32 v[32:33], v[4:5]
	v_mov_b64_e32 v[30:31], v[2:3]
	s_and_saveexec_b64 s[52:53], vcc
	s_cbranch_execz .LBB0_84
	v_or_b32_e32 v30, 24, v72
	v_mul_hi_i32_i24_e32 v31, s34, v30
	v_mul_i32_i24_e32 v30, s34, v30
	v_lshl_add_u64 v[30:31], v[30:31], 2, v[74:75]
	global_load_dwordx4 v[30:33], v[30:31], off nt
.LBB0_84:
	s_or_b64 exec, exec, s[52:53]
	v_mov_b64_e32 v[36:37], v[4:5]
	v_mov_b64_e32 v[34:35], v[2:3]
	s_and_saveexec_b64 s[52:53], vcc
	s_cbranch_execz .LBB0_86
	v_or_b32_e32 v3, 28, v72
	v_mul_hi_i32_i24_e32 v5, s34, v3
	v_mul_i32_i24_e32 v4, s34, v3
	v_lshl_add_u64 v[4:5], v[4:5], 2, v[74:75]
	global_load_dwordx4 v[34:37], v[4:5], off nt
.LBB0_86:
	s_or_b64 exec, exec, s[52:53]
	v_mov_b32_e32 v4, v2
	v_mov_b32_e32 v5, v2
	v_mov_b32_e32 v3, v2
	v_mov_b64_e32 v[40:41], v[4:5]
	v_mov_b64_e32 v[38:39], v[2:3]
	s_and_saveexec_b64 s[52:53], vcc
	s_cbranch_execz .LBB0_88
	v_or_b32_e32 v38, 32, v72
	v_mul_hi_i32_i24_e32 v39, s34, v38
	v_mul_i32_i24_e32 v38, s34, v38
	v_lshl_add_u64 v[38:39], v[38:39], 2, v[74:75]
	global_load_dwordx4 v[38:41], v[38:39], off nt
.LBB0_88:
	s_or_b64 exec, exec, s[52:53]
	v_mov_b64_e32 v[44:45], v[4:5]
	v_mov_b64_e32 v[42:43], v[2:3]
	s_and_saveexec_b64 s[52:53], vcc
	s_cbranch_execz .LBB0_90
	v_or_b32_e32 v3, 36, v72
	v_mul_hi_i32_i24_e32 v5, s34, v3
	v_mul_i32_i24_e32 v4, s34, v3
	v_lshl_add_u64 v[4:5], v[4:5], 2, v[74:75]
	global_load_dwordx4 v[42:45], v[4:5], off nt
.LBB0_90:
	s_or_b64 exec, exec, s[52:53]
	v_mov_b32_e32 v4, v2
	v_mov_b32_e32 v5, v2
	v_mov_b32_e32 v3, v2
	v_mov_b64_e32 v[48:49], v[4:5]
	v_mov_b64_e32 v[46:47], v[2:3]
	s_and_saveexec_b64 s[52:53], vcc
	s_cbranch_execz .LBB0_92
	v_or_b32_e32 v46, 40, v72
	v_mul_hi_i32_i24_e32 v47, s34, v46
	v_mul_i32_i24_e32 v46, s34, v46
	v_lshl_add_u64 v[46:47], v[46:47], 2, v[74:75]
	global_load_dwordx4 v[46:49], v[46:47], off nt
.LBB0_92:
	s_or_b64 exec, exec, s[52:53]
	v_mov_b64_e32 v[52:53], v[4:5]
	v_mov_b64_e32 v[50:51], v[2:3]
	s_and_saveexec_b64 s[52:53], vcc
	s_cbranch_execz .LBB0_94
	v_or_b32_e32 v3, 44, v72
	v_mul_hi_i32_i24_e32 v5, s34, v3
	v_mul_i32_i24_e32 v4, s34, v3
	v_lshl_add_u64 v[4:5], v[4:5], 2, v[74:75]
	global_load_dwordx4 v[50:53], v[4:5], off nt
.LBB0_94:
	s_or_b64 exec, exec, s[52:53]
	v_mov_b32_e32 v4, v2
	v_mov_b32_e32 v5, v2
	v_mov_b32_e32 v3, v2
	v_mov_b64_e32 v[56:57], v[4:5]
	v_mov_b64_e32 v[54:55], v[2:3]
	s_and_saveexec_b64 s[52:53], vcc
	s_cbranch_execz .LBB0_96
	v_or_b32_e32 v54, 48, v72
	v_mul_hi_i32_i24_e32 v55, s34, v54
	v_mul_i32_i24_e32 v54, s34, v54
	v_lshl_add_u64 v[54:55], v[54:55], 2, v[74:75]
	global_load_dwordx4 v[54:57], v[54:55], off nt
.LBB0_96:
	s_or_b64 exec, exec, s[52:53]
	v_mov_b64_e32 v[60:61], v[4:5]
	v_mov_b64_e32 v[58:59], v[2:3]
	s_and_saveexec_b64 s[52:53], vcc
	s_cbranch_execz .LBB0_98
	v_or_b32_e32 v3, 52, v72
	v_mul_hi_i32_i24_e32 v5, s34, v3
	v_mul_i32_i24_e32 v4, s34, v3
	v_lshl_add_u64 v[4:5], v[4:5], 2, v[74:75]
	global_load_dwordx4 v[58:61], v[4:5], off nt
.LBB0_98:
	s_or_b64 exec, exec, s[52:53]
	v_mov_b32_e32 v4, v2
	v_mov_b32_e32 v5, v2
	v_mov_b32_e32 v3, v2
	v_mov_b64_e32 v[64:65], v[4:5]
	v_mov_b64_e32 v[62:63], v[2:3]
	s_and_saveexec_b64 s[52:53], vcc
	s_cbranch_execz .LBB0_100
	v_or_b32_e32 v62, 56, v72
	v_mul_hi_i32_i24_e32 v63, s34, v62
	v_mul_i32_i24_e32 v62, s34, v62
	v_lshl_add_u64 v[62:63], v[62:63], 2, v[74:75]
	global_load_dwordx4 v[62:65], v[62:63], off nt
.LBB0_100:
	s_or_b64 exec, exec, s[52:53]
	v_mov_b64_e32 v[68:69], v[4:5]
	v_mov_b64_e32 v[66:67], v[2:3]
	s_and_saveexec_b64 s[52:53], vcc
	s_cbranch_execz .LBB0_102
	v_or_b32_e32 v3, 60, v72
	v_mul_hi_i32_i24_e32 v5, s34, v3
	v_mul_i32_i24_e32 v4, s34, v3
	v_lshl_add_u64 v[4:5], v[4:5], 2, v[74:75]
	global_load_dwordx4 v[66:69], v[4:5], off nt

.LBB0_107:
	global_load_dwordx4 v[18:21], v[6:7], off offset:-3072 nt
	global_load_dwordx4 v[22:25], v[6:7], off offset:-2048 nt
	global_load_dwordx4 v[26:29], v[6:7], off offset:-1024 nt
	global_load_dwordx4 v[30:33], v[6:7], off nt
	s_waitcnt vmcnt(3)
	v_mul_f32_e32 v5, v19, v19
	s_waitcnt lgkmcnt(0)
	v_mul_f32_e32 v17, v21, v21
	s_waitcnt vmcnt(2)
	v_mul_f32_e32 v34, v23, v23
	v_mul_f32_e32 v35, v25, v25
	s_waitcnt vmcnt(1)
	v_mul_f32_e32 v36, v27, v27
	v_mul_f32_e32 v37, v29, v29
	v_fmac_f32_e32 v17, v20, v20
	v_fmac_f32_e32 v34, v22, v22
	v_fmac_f32_e32 v35, v24, v24
	v_fmac_f32_e32 v5, v18, v18
	s_waitcnt vmcnt(0)
	v_mul_f32_e32 v38, v31, v31
	v_mul_f32_e32 v39, v33, v33
	v_fmac_f32_e32 v36, v26, v26
	v_fmac_f32_e32 v37, v28, v28
	v_add_f32_e32 v34, v34, v35
	v_add_f32_e32 v5, v5, v17
	v_fmac_f32_e32 v38, v30, v30
	v_fmac_f32_e32 v39, v32, v32
	v_add_f32_e32 v35, v36, v37
	v_add_f32_e32 v5, v5, v34
	v_add_f32_e32 v36, v38, v39
	v_add_f32_e32 v5, v5, v35
	v_add_f32_e32 v5, v5, v36
	ds_bpermute_b32 v17, v11, v5
	v_cvt_pk_bf16_f32 v18, v18, v19
	v_cvt_pk_bf16_f32 v19, v20, v21
	global_store_dwordx2 v[8:9], v[18:19], off offset:-1024
	v_cvt_pk_bf16_f32 v18, v22, v23
	s_waitcnt lgkmcnt(0)
	v_add_f32_e32 v5, v5, v17
	ds_bpermute_b32 v17, v12, v5
	v_cvt_pk_bf16_f32 v19, v24, v25
	global_store_dwordx2 v[8:9], v[18:19], off offset:-512
	v_cvt_pk_bf16_f32 v18, v26, v27
	v_cvt_pk_bf16_f32 v19, v28, v29
	s_waitcnt lgkmcnt(0)
	v_add_f32_e32 v5, v5, v17
	ds_bpermute_b32 v17, v13, v5
	global_store_dwordx2 v[8:9], v[18:19], off
	v_cvt_pk_bf16_f32 v18, v30, v31
	v_cvt_pk_bf16_f32 v19, v32, v33
	global_store_dwordx2 v[8:9], v[18:19], off offset:512
	s_waitcnt lgkmcnt(0)
	v_add_f32_e32 v5, v5, v17
	ds_bpermute_b32 v17, v14, v5
	s_waitcnt lgkmcnt(0)
	v_add_f32_e32 v5, v5, v17
	ds_bpermute_b32 v17, v15, v5
	s_waitcnt lgkmcnt(0)
	v_add_f32_e32 v5, v5, v17
	ds_bpermute_b32 v17, v16, v5
	s_and_saveexec_b64 s[16:17], vcc
	s_cbranch_execz .LBB0_106
	s_waitcnt lgkmcnt(0)
	v_add_f32_e32 v5, v5, v17
	v_mul_f32_e32 v5, 0x49800000, v5
	v_trunc_f32_e32 v5, v5
	v_mul_f32_e32 v17, 0x2f800000, v5
	v_floor_f32_e32 v17, v17
	v_fmac_f32_e32 v5, 0xcf800000, v17
	v_cvt_u32_f32_e32 v18, v5
	v_cvt_u32_f32_e32 v19, v17
	global_store_dwordx2 v3, v[18:19], s[0:1]
	s_branch .LBB0_106
